# convert_phase: 8 element loads per tile batched behind one wait (plus silu fill batching from previous version)
# speedup vs baseline: 1.0542x; 1.0096x over previous
; __device__ __forceinline__ float silu_f(float v) { return v * __builtin_amdgcn_rcpf(1.f + __expf(-v)); }
; __device__ void mod_phase(const Params& p, float* sm, int w0) {
;     ...
;     __syncthreads();
;     for (int i = tid; i < 33 * 1024; i += NTHREADS) { const int bi = i >> 10, d = i & 1023; const float cv = bi < 32 ? p.c[bi * 1024 + d] : p.c_ctx[d]; sm[i] = silu_f(cv); }
;     __syncthreads();
.LBB0_39:
	s_movk_i32 s28, 0
.Lsilu_loop:
	s_mov_b32 s31, 0
	v_add_u32_e32 v56, 0x0, v13
	v_cmp_gt_i32_e64 s[6:7], s74, v56
	v_and_b32_e32 v56, 0x3ff, v56
	v_lshlrev_b32_e32 v56, 2, v56
	v_mov_b32_e32 v57, v1
	v_lshl_add_u64 v[56:57], s[14:15], 0, v[56:57]
	s_mov_b32 s30, 0x0
	v_lshl_add_u64 v[68:69], v[10:11], 0, s[30:31]
	v_cndmask_b32_e64 v57, v57, v69, s[6:7]
	v_cndmask_b32_e64 v56, v56, v68, s[6:7]
	global_load_dword v70, v[56:57], off
	v_add_u32_e32 v58, 0x200, v13
	v_cmp_gt_i32_e64 s[6:7], s74, v58
	v_and_b32_e32 v58, 0x3ff, v58
	v_lshlrev_b32_e32 v58, 2, v58
	v_mov_b32_e32 v59, v1
	v_lshl_add_u64 v[58:59], s[14:15], 0, v[58:59]
	s_mov_b32 s30, 0x800
	v_lshl_add_u64 v[68:69], v[10:11], 0, s[30:31]
	v_cndmask_b32_e64 v59, v59, v69, s[6:7]
	v_cndmask_b32_e64 v58, v58, v68, s[6:7]
	global_load_dword v71, v[58:59], off
	v_add_u32_e32 v60, 0x400, v13
	v_cmp_gt_i32_e64 s[6:7], s74, v60
	v_and_b32_e32 v60, 0x3ff, v60
	v_lshlrev_b32_e32 v60, 2, v60
	v_mov_b32_e32 v61, v1
	v_lshl_add_u64 v[60:61], s[14:15], 0, v[60:61]
	s_mov_b32 s30, 0x1000
	v_lshl_add_u64 v[68:69], v[10:11], 0, s[30:31]
	v_cndmask_b32_e64 v61, v61, v69, s[6:7]
	v_cndmask_b32_e64 v60, v60, v68, s[6:7]
	global_load_dword v72, v[60:61], off
	v_add_u32_e32 v62, 0x600, v13
	v_cmp_gt_i32_e64 s[6:7], s74, v62
	v_and_b32_e32 v62, 0x3ff, v62
	v_lshlrev_b32_e32 v62, 2, v62
	v_mov_b32_e32 v63, v1
	v_lshl_add_u64 v[62:63], s[14:15], 0, v[62:63]
	s_mov_b32 s30, 0x1800
	v_lshl_add_u64 v[68:69], v[10:11], 0, s[30:31]
	v_cndmask_b32_e64 v63, v63, v69, s[6:7]
	v_cndmask_b32_e64 v62, v62, v68, s[6:7]
	global_load_dword v73, v[62:63], off
	v_add_u32_e32 v64, 0x800, v13
	v_cmp_gt_i32_e64 s[6:7], s74, v64
	v_and_b32_e32 v64, 0x3ff, v64
	v_lshlrev_b32_e32 v64, 2, v64
	v_mov_b32_e32 v65, v1
	v_lshl_add_u64 v[64:65], s[14:15], 0, v[64:65]
	s_mov_b32 s30, 0x2000
	v_lshl_add_u64 v[68:69], v[10:11], 0, s[30:31]
	v_cndmask_b32_e64 v65, v65, v69, s[6:7]
	v_cndmask_b32_e64 v64, v64, v68, s[6:7]
	global_load_dword v74, v[64:65], off
	v_add_u32_e32 v66, 0xa00, v13
	v_cmp_gt_i32_e64 s[6:7], s74, v66
	v_and_b32_e32 v66, 0x3ff, v66
	v_lshlrev_b32_e32 v66, 2, v66
	v_mov_b32_e32 v67, v1
	v_lshl_add_u64 v[66:67], s[14:15], 0, v[66:67]
	s_mov_b32 s30, 0x2800
	v_lshl_add_u64 v[68:69], v[10:11], 0, s[30:31]
	v_cndmask_b32_e64 v67, v67, v69, s[6:7]
	v_cndmask_b32_e64 v66, v66, v68, s[6:7]
	global_load_dword v75, v[66:67], off
	s_waitcnt vmcnt(5)
	v_mul_f32_e32 v15, 0xbfb8aa3b, v70
	v_exp_f32_e32 v15, v15
	s_nop 0
	v_add_f32_e32 v14, 1.0, v15
	v_rcp_f32_e32 v15, v14
	s_nop 0
	v_mul_f32_e32 v70, v70, v15
	ds_write_b32 v12, v70
	s_waitcnt vmcnt(4)
	v_mul_f32_e32 v15, 0xbfb8aa3b, v71
	v_exp_f32_e32 v15, v15
	s_nop 0
	v_add_f32_e32 v14, 1.0, v15
	v_rcp_f32_e32 v15, v14
	s_nop 0
	v_mul_f32_e32 v71, v71, v15
	ds_write_b32 v12, v71 offset:2048
	s_waitcnt vmcnt(3)
	v_mul_f32_e32 v15, 0xbfb8aa3b, v72
	v_exp_f32_e32 v15, v15
	s_nop 0
	v_add_f32_e32 v14, 1.0, v15
	v_rcp_f32_e32 v15, v14
	s_nop 0
	v_mul_f32_e32 v72, v72, v15
	ds_write_b32 v12, v72 offset:4096
	s_waitcnt vmcnt(2)
	v_mul_f32_e32 v15, 0xbfb8aa3b, v73
	v_exp_f32_e32 v15, v15
	s_nop 0
	v_add_f32_e32 v14, 1.0, v15
	v_rcp_f32_e32 v15, v14
	s_nop 0
	v_mul_f32_e32 v73, v73, v15
	ds_write_b32 v12, v73 offset:6144
	s_waitcnt vmcnt(1)
	v_mul_f32_e32 v15, 0xbfb8aa3b, v74
	v_exp_f32_e32 v15, v15
	s_nop 0
	v_add_f32_e32 v14, 1.0, v15
	v_rcp_f32_e32 v15, v14
	s_nop 0
	v_mul_f32_e32 v74, v74, v15
	ds_write_b32 v12, v74 offset:8192
	s_waitcnt vmcnt(0)
	v_mul_f32_e32 v15, 0xbfb8aa3b, v75
	v_exp_f32_e32 v15, v15
	s_nop 0
	v_add_f32_e32 v14, 1.0, v15
	v_rcp_f32_e32 v15, v14
	s_nop 0
	v_mul_f32_e32 v75, v75, v15
	ds_write_b32 v12, v75 offset:10240
	v_add_u32_e32 v13, 0xc00, v13
	s_mov_b64 s[6:7], 0x3000
	v_lshl_add_u64 v[10:11], v[10:11], 0, s[6:7]
	v_add_u32_e32 v12, 0x3000, v12
	s_add_i32 s28, s28, 1
	s_cmp_lt_u32 s28, 11
	s_cbranch_scc1 .Lsilu_loop

; __device__ __forceinline__ unsigned pk2(float lo, float hi) { const f2_t v = {lo, hi}; return __builtin_bit_cast(unsigned, __builtin_convertvector(v, bf2_t)); }
; __device__ void convert_phase(const Params& p, int l, int tbeg, int tend, float* sm, int w0) {
;     ...
;     __syncthreads();
;     { const int nn = tid >> 3, kk0 = (tid & 7) * 8; u32x4 w;
;       w.x = pk2(sm[(kk0 + 0) * 65 + nn], sm[(kk0 + 1) * 65 + nn]); w.y = pk2(sm[(kk0 + 2) * 65 + nn], sm[(kk0 + 3) * 65 + nn]);
;       w.z = pk2(sm[(kk0 + 4) * 65 + nn], sm[(kk0 + 5) * 65 + nn]); w.w = pk2(sm[(kk0 + 6) * 65 + nn], sm[(kk0 + 7) * 65 + nn]);
;       *(u32x4*)(dst + (long)(n0 + nn) * Kp + k0 + kk0) = w; }
.LBB0_57:
	s_waitcnt lgkmcnt(0)
	s_barrier
	ds_read2_b32 v[6:7], v11 offset1:65
	ds_read2_b32 v[8:9], v11 offset0:130 offset1:195
	v_add_u32_e32 v0, 0x400, v11
	ds_read2_b32 v[14:15], v0 offset0:4 offset1:69
	ds_read2_b32 v[16:17], v0 offset0:134 offset1:199
	v_add_u32_e32 v0, s13, v10
	v_ashrrev_i32_e32 v5, 31, v0
	s_waitcnt lgkmcnt(3)
	v_cvt_pk_bf16_f32 v6, v6, v7
	s_waitcnt lgkmcnt(2)
	v_cvt_pk_bf16_f32 v7, v8, v9
	s_waitcnt lgkmcnt(1)
	v_cvt_pk_bf16_f32 v8, v14, v15
	v_mul_lo_u32 v5, s0, v5
	v_mul_lo_u32 v13, s1, v0
	v_mad_u64_u32 v[14:15], s[0:1], s0, v0, 0
	v_add3_u32 v15, v15, v5, v13
	v_lshl_add_u64 v[14:15], v[14:15], 1, s[10:11]
	s_ashr_i32 s13, s12, 31
	v_lshl_add_u64 v[14:15], s[12:13], 1, v[14:15]
	v_mov_b32_e32 v5, v1
	s_add_i32 s2, s2, s62
	s_waitcnt lgkmcnt(0)
	v_cvt_pk_bf16_f32 v9, v16, v17
	v_lshl_add_u64 v[14:15], v[14:15], 0, v[4:5]
	s_cmpk_lt_i32 s2, 0xbb0
	global_store_dwordx4 v[14:15], v[6:9], off
	s_cbranch_scc0 .LBB0_109

; __device__ void convert_phase(const Params& p, int l, int tbeg, int tend, float* sm, int w0) {
;     ...
;     __syncthreads();
; #pragma unroll
;     for (int i = 0; i < 8; ++i) {
;       const int kk = (tid >> 6) + 8 * i, nn = tid & 63; float v = 0.f;
;       if (k0 + kk < K && n0 + nn < N) { v = src[(long)(k0 + kk) * N + c0 + nn]; if (ksc) v *= ksc[k0 + kk]; }
;       sm[kk * 65 + nn] = v;
;     }
.LBB0_84:
	s_mul_i32 s12, s12, s19
	s_sub_i32 s4, s15, s12
	s_ashr_i32 s15, s14, 31
	s_lshl_b32 s12, s4, 6
	s_lshl_b64 s[14:15], s[14:15], 2
	s_waitcnt lgkmcnt(0)
	s_add_u32 s6, s6, s14
	v_or_b32_e32 v0, s13, v2
	s_addc_u32 s7, s7, s15
	v_cmp_gt_i32_e64 s[4:5], s17, v0
	v_lshlrev_b32_e32 v0, 2, v2
	s_cmp_lg_u64 s[8:9], 0
	v_lshl_add_u64 v[8:9], s[6:7], 0, v[0:1]
	s_cselect_b64 s[6:7], -1, 0
	v_add_u32_e32 v6, s12, v3
	v_cmp_gt_i32_e32 vcc, s18, v6
	v_cndmask_b32_e64 v5, 0, 1, s[6:7]
	s_and_b64 s[20:21], vcc, s[4:5]
	v_mov_b32_e32 v0, 0
	v_cmp_ne_u32_e64 s[6:7], 1, v5
	v_mov_b32_e32 v5, 0
	s_barrier
	v_ashrrev_i32_e32 v7, 31, v6
	v_lshl_add_u64 v[212:213], v[6:7], 2, s[8:9]
	v_mov_b32_e32 v208, v6
	v_cmp_gt_i32_e64 s[46:47], s18, v208
	v_mad_u64_u32 v[192:193], s[50:51], v208, s17, 0
	v_ashrrev_i32_e32 v209, 31, v208
	v_mov_b32_e32 v210, v193
	v_mov_b32_e32 v211, v1
	s_and_b64 s[46:47], s[46:47], s[4:5]
	v_mad_u64_u32 v[210:211], s[50:51], v209, s17, v[210:211]
	v_mov_b32_e32 v176, 0
	v_mov_b32_e32 v193, v210
	v_mov_b32_e32 v184, 1.0
	v_lshl_add_u64 v[192:193], v[192:193], 2, v[8:9]
	s_and_saveexec_b64 s[48:49], s[46:47]
	global_load_dword v176, v[192:193], off
	s_and_b64 vcc, exec, s[6:7]
	s_cbranch_vccnz .Lcv0_nk0
	global_load_dword v184, v[212:213], off
.Lcv0_nk0:
	s_or_b64 exec, exec, s[48:49]
	v_add_u32_e32 v208, 8, v6
	v_cmp_gt_i32_e64 s[46:47], s18, v208
	v_mad_u64_u32 v[194:195], s[50:51], v208, s17, 0
	v_ashrrev_i32_e32 v209, 31, v208
	v_mov_b32_e32 v210, v195
	v_mov_b32_e32 v211, v1
	s_and_b64 s[46:47], s[46:47], s[4:5]
	v_mad_u64_u32 v[210:211], s[50:51], v209, s17, v[210:211]
	v_mov_b32_e32 v177, 0
	v_mov_b32_e32 v195, v210
	v_mov_b32_e32 v185, 1.0
	v_lshl_add_u64 v[194:195], v[194:195], 2, v[8:9]
	s_and_saveexec_b64 s[48:49], s[46:47]
	global_load_dword v177, v[194:195], off
	s_and_b64 vcc, exec, s[6:7]
	s_cbranch_vccnz .Lcv0_nk1
	global_load_dword v185, v[212:213], off offset:32
.Lcv0_nk1:
	s_or_b64 exec, exec, s[48:49]
	v_add_u32_e32 v208, 16, v6
	v_cmp_gt_i32_e64 s[46:47], s18, v208
	v_mad_u64_u32 v[196:197], s[50:51], v208, s17, 0
	v_ashrrev_i32_e32 v209, 31, v208
	v_mov_b32_e32 v210, v197
	v_mov_b32_e32 v211, v1
	s_and_b64 s[46:47], s[46:47], s[4:5]
	v_mad_u64_u32 v[210:211], s[50:51], v209, s17, v[210:211]
	v_mov_b32_e32 v178, 0
	v_mov_b32_e32 v197, v210
	v_mov_b32_e32 v186, 1.0
	v_lshl_add_u64 v[196:197], v[196:197], 2, v[8:9]
	s_and_saveexec_b64 s[48:49], s[46:47]
	global_load_dword v178, v[196:197], off
	s_and_b64 vcc, exec, s[6:7]
	s_cbranch_vccnz .Lcv0_nk2
	global_load_dword v186, v[212:213], off offset:64
.Lcv0_nk2:
	s_or_b64 exec, exec, s[48:49]
	v_add_u32_e32 v208, 24, v6
	v_cmp_gt_i32_e64 s[46:47], s18, v208
	v_mad_u64_u32 v[198:199], s[50:51], v208, s17, 0
	v_ashrrev_i32_e32 v209, 31, v208
	v_mov_b32_e32 v210, v199
	v_mov_b32_e32 v211, v1
	s_and_b64 s[46:47], s[46:47], s[4:5]
	v_mad_u64_u32 v[210:211], s[50:51], v209, s17, v[210:211]
	v_mov_b32_e32 v179, 0
	v_mov_b32_e32 v199, v210
	v_mov_b32_e32 v187, 1.0
	v_lshl_add_u64 v[198:199], v[198:199], 2, v[8:9]
	s_and_saveexec_b64 s[48:49], s[46:47]
	global_load_dword v179, v[198:199], off
	s_and_b64 vcc, exec, s[6:7]
	s_cbranch_vccnz .Lcv0_nk3
	global_load_dword v187, v[212:213], off offset:96
.Lcv0_nk3:
	s_or_b64 exec, exec, s[48:49]
	v_add_u32_e32 v208, 32, v6
	v_cmp_gt_i32_e64 s[46:47], s18, v208
	v_mad_u64_u32 v[200:201], s[50:51], v208, s17, 0
	v_ashrrev_i32_e32 v209, 31, v208
	v_mov_b32_e32 v210, v201
	v_mov_b32_e32 v211, v1
	s_and_b64 s[46:47], s[46:47], s[4:5]
	v_mad_u64_u32 v[210:211], s[50:51], v209, s17, v[210:211]
	v_mov_b32_e32 v180, 0
	v_mov_b32_e32 v201, v210
	v_mov_b32_e32 v188, 1.0
	v_lshl_add_u64 v[200:201], v[200:201], 2, v[8:9]
	s_and_saveexec_b64 s[48:49], s[46:47]
	global_load_dword v180, v[200:201], off
	s_and_b64 vcc, exec, s[6:7]
	s_cbranch_vccnz .Lcv0_nk4
	global_load_dword v188, v[212:213], off offset:128
.Lcv0_nk4:
	s_or_b64 exec, exec, s[48:49]
	v_add_u32_e32 v208, 40, v6
	v_cmp_gt_i32_e64 s[46:47], s18, v208
	v_mad_u64_u32 v[202:203], s[50:51], v208, s17, 0
	v_ashrrev_i32_e32 v209, 31, v208
	v_mov_b32_e32 v210, v203
	v_mov_b32_e32 v211, v1
	s_and_b64 s[46:47], s[46:47], s[4:5]
	v_mad_u64_u32 v[210:211], s[50:51], v209, s17, v[210:211]
	v_mov_b32_e32 v181, 0
	v_mov_b32_e32 v203, v210
	v_mov_b32_e32 v189, 1.0
	v_lshl_add_u64 v[202:203], v[202:203], 2, v[8:9]
	s_and_saveexec_b64 s[48:49], s[46:47]
	global_load_dword v181, v[202:203], off
	s_and_b64 vcc, exec, s[6:7]
	s_cbranch_vccnz .Lcv0_nk5
	global_load_dword v189, v[212:213], off offset:160
.Lcv0_nk5:
	s_or_b64 exec, exec, s[48:49]
	v_add_u32_e32 v208, 48, v6
	v_cmp_gt_i32_e64 s[46:47], s18, v208
	v_mad_u64_u32 v[204:205], s[50:51], v208, s17, 0
	v_ashrrev_i32_e32 v209, 31, v208
	v_mov_b32_e32 v210, v205
	v_mov_b32_e32 v211, v1
	s_and_b64 s[46:47], s[46:47], s[4:5]
	v_mad_u64_u32 v[210:211], s[50:51], v209, s17, v[210:211]
	v_mov_b32_e32 v182, 0
	v_mov_b32_e32 v205, v210
	v_mov_b32_e32 v190, 1.0
	v_lshl_add_u64 v[204:205], v[204:205], 2, v[8:9]
	s_and_saveexec_b64 s[48:49], s[46:47]
	global_load_dword v182, v[204:205], off
	s_and_b64 vcc, exec, s[6:7]
	s_cbranch_vccnz .Lcv0_nk6
	global_load_dword v190, v[212:213], off offset:192
.Lcv0_nk6:
	s_or_b64 exec, exec, s[48:49]
	v_add_u32_e32 v208, 56, v6
	v_cmp_gt_i32_e64 s[46:47], s18, v208
	v_mad_u64_u32 v[206:207], s[50:51], v208, s17, 0
	v_ashrrev_i32_e32 v209, 31, v208
	v_mov_b32_e32 v210, v207
	v_mov_b32_e32 v211, v1
	s_and_b64 s[46:47], s[46:47], s[4:5]
	v_mad_u64_u32 v[210:211], s[50:51], v209, s17, v[210:211]
	v_mov_b32_e32 v183, 0
	v_mov_b32_e32 v207, v210
	v_mov_b32_e32 v191, 1.0
	v_lshl_add_u64 v[206:207], v[206:207], 2, v[8:9]
	s_and_saveexec_b64 s[48:49], s[46:47]
	global_load_dword v183, v[206:207], off
	s_and_b64 vcc, exec, s[6:7]
	s_cbranch_vccnz .Lcv0_nk7
	global_load_dword v191, v[212:213], off offset:224
.Lcv0_nk7:
	s_or_b64 exec, exec, s[48:49]
	s_waitcnt vmcnt(0)
	v_mul_f32_e32 v176, v176, v184
	v_mul_f32_e32 v177, v177, v185
	v_mul_f32_e32 v178, v178, v186
	v_mul_f32_e32 v179, v179, v187
	v_mul_f32_e32 v180, v180, v188
	v_mul_f32_e32 v181, v181, v189
	v_mul_f32_e32 v182, v182, v190
	v_mul_f32_e32 v183, v183, v191
	ds_write_b32 v12, v176
	ds_write_b32 v12, v177 offset:2080
	ds_write_b32 v12, v178 offset:4160
	ds_write_b32 v12, v179 offset:6240
	ds_write_b32 v12, v180 offset:8320
	ds_write_b32 v12, v181 offset:10400
	ds_write_b32 v12, v182 offset:12480
	ds_write_b32 v12, v183 offset:14560
	s_branch .LBB0_57

; __device__ __forceinline__ unsigned pk2(float lo, float hi) { const f2_t v = {lo, hi}; return __builtin_bit_cast(unsigned, __builtin_convertvector(v, bf2_t)); }
; __device__ void convert_phase(const Params& p, int l, int tbeg, int tend, float* sm, int w0) {
;     ...
;     __syncthreads();
;     { const int nn = tid >> 3, kk0 = (tid & 7) * 8; u32x4 w;
;       w.x = pk2(sm[(kk0 + 0) * 65 + nn], sm[(kk0 + 1) * 65 + nn]); w.y = pk2(sm[(kk0 + 2) * 65 + nn], sm[(kk0 + 3) * 65 + nn]);
;       w.z = pk2(sm[(kk0 + 4) * 65 + nn], sm[(kk0 + 5) * 65 + nn]); w.w = pk2(sm[(kk0 + 6) * 65 + nn], sm[(kk0 + 7) * 65 + nn]);
;       *(u32x4*)(dst + (long)(n0 + nn) * Kp + k0 + kk0) = w; }
.LBB0_424:
	s_waitcnt lgkmcnt(0)
	s_barrier
	ds_read2_b32 v[6:7], v11 offset1:65
	ds_read2_b32 v[8:9], v11 offset0:130 offset1:195
	v_add_u32_e32 v0, 0x400, v11
	ds_read2_b32 v[14:15], v0 offset0:134 offset1:199
	s_ashr_i32 s83, s82, 31
	s_waitcnt lgkmcnt(2)
	v_cvt_pk_bf16_f32 v6, v6, v7
	s_waitcnt lgkmcnt(1)
	v_cvt_pk_bf16_f32 v7, v8, v9
	ds_read2_b32 v[8:9], v0 offset0:4 offset1:69
	v_add_u32_e32 v0, s0, v10
	v_ashrrev_i32_e32 v5, 31, v0
	v_mul_lo_u32 v5, s66, v5
	v_mul_lo_u32 v13, s67, v0
	s_waitcnt lgkmcnt(0)
	v_cvt_pk_bf16_f32 v8, v8, v9
	v_cvt_pk_bf16_f32 v9, v14, v15
	v_mad_u64_u32 v[14:15], s[0:1], s66, v0, 0
	v_add3_u32 v15, v15, v5, v13
	v_lshl_add_u64 v[14:15], v[14:15], 1, s[8:9]
	v_lshl_add_u64 v[14:15], s[82:83], 1, v[14:15]
	v_mov_b32_e32 v5, v1
	s_add_i32 s2, s2, s62
	v_lshl_add_u64 v[14:15], v[14:15], 0, v[4:5]
	s_cmpk_lt_i32 s2, 0x370
	global_store_dwordx4 v[14:15], v[6:9], off
	s_cbranch_scc0 .LBB0_463

; __device__ void convert_phase(const Params& p, int l, int tbeg, int tend, float* sm, int w0) {
;     ...
;     const float* src; bf16_t* dst; int K, N, Kp, nkt, tt; const float* ksc = nullptr; int mode = 0;
;     if (task < T0)      { tt = task;      src = p.w_in + (long)l * 1024 * 1984; dst = p.Wt_in; K = 1024; N = 1984; Kp = 1024; nkt = 16; }
;     else if (task < T1) { tt = task - T0; src = p.w_uq + (long)l * 256 * 768; dst = p.Wt_uq; K = 256; N = 768; Kp = 256; nkt = 4; ksc = p.qn_g + l * 256; }
;     else if (task < T2) { tt = task - T1; src = p.w_uk + (long)l * 128 * 512; dst = p.Wt_uk; K = 128; N = 512; Kp = 256; nkt = 4; ksc = p.kvn_g + l * 128; }
;     else if (task < T3) { tt = task - T2; src = p.w_uv + (long)l * 128 * 512; dst = p.Wt_uv; K = 128; N = 512; Kp = 256; nkt = 4; ksc = p.kvn_g + l * 128; }
;     else if (task < T4) { tt = task - T3; src = p.w_out + (long)l * 1024 * 1024; dst = p.Wt_out; K = 1024; N = 1024; Kp = 1024; nkt = 16; }
;     else if (task < T5) { tt = task - T4; src = p.ffn_up + (long)l * 1024 * 5632; dst = p.Wt_up; K = 1024; N = 5632; Kp = 1024; nkt = 16; mode = 1; }
;     else                { tt = task - T5; src = p.ffn_down + (long)l * 2816 * 1024; dst = p.Wt_down; K = 2816; N = 1024; Kp = 2816; nkt = 44; }
;     const int n0 = (tt / nkt) * 64, k0 = (tt % nkt) * 64;
;     int c0 = n0;
;     if (mode == 1) { const int pn = n0 >> 8, j = n0 & 255; c0 = j < 128 ? pn * 128 + j : 2816 + pn * 128 + (j - 128); }
;     __syncthreads();
; #pragma unroll
;     for (int i = 0; i < 8; ++i) {
;       const int kk = (tid >> 6) + 8 * i, nn = tid & 63; float v = 0.f;
;       if (k0 + kk < K && n0 + nn < N) { v = src[(long)(k0 + kk) * N + c0 + nn]; if (ksc) v *= ksc[k0 + kk]; }
;       sm[kk * 65 + nn] = v;
;     }
.LBB0_438:
	v_cvt_f32_u32_e32 v0, s5
	s_sub_i32 s12, 0, s5
	s_abs_i32 s1, s4
	s_ashr_i32 s0, s4, 31
	v_rcp_iflag_f32_e32 v0, v0
	s_barrier
	v_mul_f32_e32 v0, 0x4f7ffffe, v0
	v_cvt_u32_f32_e32 v0, v0
	s_nop 0
	v_readfirstlane_b32 s13, v0
	s_mul_i32 s12, s12, s13
	s_mul_hi_u32 s12, s13, s12
	s_add_i32 s13, s13, s12
	s_mul_hi_u32 s12, s1, s13
	s_mul_i32 s13, s12, s5
	s_sub_i32 s1, s1, s13
	s_add_i32 s20, s12, 1
	s_sub_i32 s13, s1, s5
	s_cmp_ge_u32 s1, s5
	s_cselect_b32 s12, s20, s12
	s_cselect_b32 s1, s13, s1
	s_add_i32 s13, s12, 1
	s_cmp_ge_u32 s1, s5
	s_cselect_b32 s1, s13, s12
	s_xor_b32 s1, s1, s0
	s_sub_i32 s1, s1, s0
	s_lshl_b32 s0, s1, 6
	s_mul_i32 s1, s1, s5
	s_sub_i32 s1, s4, s1
	s_lshl_b32 s82, s1, 6
	s_ashr_i32 s1, s0, 31
	s_lshl_b64 s[12:13], s[0:1], 2
	s_add_u32 s6, s6, s12
	v_or_b32_e32 v0, s0, v2
	s_addc_u32 s7, s7, s13
	v_cmp_gt_i32_e64 s[4:5], s17, v0
	v_lshlrev_b32_e32 v0, 2, v2
	s_cmp_lg_u64 s[80:81], 0
	v_lshl_add_u64 v[8:9], s[6:7], 0, v[0:1]
	s_cselect_b64 s[6:7], -1, 0
	v_add_u32_e32 v6, s82, v3
	v_cmp_gt_i32_e32 vcc, s18, v6
	v_cndmask_b32_e64 v5, 0, 1, s[6:7]
	s_and_b64 s[20:21], vcc, s[4:5]
	v_mov_b32_e32 v0, 0
	v_cmp_ne_u32_e64 s[6:7], 1, v5
	v_mov_b32_e32 v5, 0
	s_load_dwordx2 s[8:9], s[8:9], 0x0
	v_ashrrev_i32_e32 v7, 31, v6
	v_lshl_add_u64 v[212:213], v[6:7], 2, s[80:81]
	v_mov_b32_e32 v208, v6
	v_cmp_gt_i32_e64 s[46:47], s18, v208
	v_mad_u64_u32 v[192:193], s[50:51], v208, s17, 0
	v_ashrrev_i32_e32 v209, 31, v208
	v_mov_b32_e32 v210, v193
	v_mov_b32_e32 v211, v1
	s_and_b64 s[46:47], s[46:47], s[4:5]
	v_mad_u64_u32 v[210:211], s[50:51], v209, s17, v[210:211]
	v_mov_b32_e32 v176, 0
	v_mov_b32_e32 v193, v210
	v_mov_b32_e32 v184, 1.0
	v_lshl_add_u64 v[192:193], v[192:193], 2, v[8:9]
	s_and_saveexec_b64 s[48:49], s[46:47]
	global_load_dword v176, v[192:193], off
	s_and_b64 vcc, exec, s[6:7]
	s_cbranch_vccnz .Lcv1_nk0
	global_load_dword v184, v[212:213], off

; __device__ __forceinline__ unsigned pk2(float lo, float hi) { const f2_t v = {lo, hi}; return __builtin_bit_cast(unsigned, __builtin_convertvector(v, bf2_t)); }
; __device__ void convert_phase(const Params& p, int l, int tbeg, int tend, float* sm, int w0) {
;     ...
;     __syncthreads();
;     { const int nn = tid >> 3, kk0 = (tid & 7) * 8; u32x4 w;
;       w.x = pk2(sm[(kk0 + 0) * 65 + nn], sm[(kk0 + 1) * 65 + nn]); w.y = pk2(sm[(kk0 + 2) * 65 + nn], sm[(kk0 + 3) * 65 + nn]);
;       w.z = pk2(sm[(kk0 + 4) * 65 + nn], sm[(kk0 + 5) * 65 + nn]); w.w = pk2(sm[(kk0 + 6) * 65 + nn], sm[(kk0 + 7) * 65 + nn]);
;       *(u32x4*)(dst + (long)(n0 + nn) * Kp + k0 + kk0) = w; }
.LBB0_940:
	s_waitcnt lgkmcnt(0)
	s_barrier
	ds_read2_b32 v[6:7], v11 offset1:65
	ds_read2_b32 v[8:9], v11 offset0:130 offset1:195
	v_add_u32_e32 v0, 0x400, v11
	ds_read2_b32 v[14:15], v0 offset0:134 offset1:199
	s_add_i32 s2, s2, s62
	s_waitcnt lgkmcnt(2)
	v_cvt_pk_bf16_f32 v6, v6, v7
	s_waitcnt lgkmcnt(1)
	v_cvt_pk_bf16_f32 v7, v8, v9
	ds_read2_b32 v[8:9], v0 offset0:4 offset1:69
	v_add_u32_e32 v0, s9, v10
	v_ashrrev_i32_e32 v5, 31, v0
	v_mul_lo_u32 v5, s80, v5
	v_mul_lo_u32 v13, s81, v0
	s_waitcnt lgkmcnt(0)
	v_cvt_pk_bf16_f32 v8, v8, v9
	v_cvt_pk_bf16_f32 v9, v14, v15
	v_mad_u64_u32 v[14:15], s[4:5], s80, v0, 0
	v_add3_u32 v15, v15, v5, v13
	v_lshl_add_u64 v[14:15], v[14:15], 1, s[0:1]
	s_ashr_i32 s9, s8, 31
	v_lshl_add_u64 v[14:15], s[8:9], 1, v[14:15]
	v_mov_b32_e32 v5, v1
	s_add_i32 s17, s17, s62
	s_add_i32 s0, s2, 0x8f0
	v_lshl_add_u64 v[14:15], v[14:15], 0, v[4:5]
	s_cmpk_lt_i32 s0, 0xbb0
	global_store_dwordx4 v[14:15], v[6:9], off
	s_cbranch_scc0 .LBB0_989

; __device__ void convert_phase(const Params& p, int l, int tbeg, int tend, float* sm, int w0) {
;     ...
;     __syncthreads();
; #pragma unroll
;     for (int i = 0; i < 8; ++i) {
;       const int kk = (tid >> 6) + 8 * i, nn = tid & 63; float v = 0.f;
;       if (k0 + kk < K && n0 + nn < N) { v = src[(long)(k0 + kk) * N + c0 + nn]; if (ksc) v *= ksc[k0 + kk]; }
;       sm[kk * 65 + nn] = v;
;     }
.LBB0_964:
	s_mul_i32 s8, s8, s21
	s_sub_i32 s4, s22, s8
	s_ashr_i32 s11, s10, 31
	s_lshl_b32 s8, s4, 6
	s_lshl_b64 s[10:11], s[10:11], 2
	s_add_u32 s6, s6, s10
	v_or_b32_e32 v0, s9, v2
	s_addc_u32 s7, s7, s11
	v_cmp_gt_i32_e64 s[4:5], s18, v0
	v_lshlrev_b32_e32 v0, 2, v2
	s_cmp_lg_u64 s[82:83], 0
	v_lshl_add_u64 v[8:9], s[6:7], 0, v[0:1]
	s_cselect_b64 s[6:7], -1, 0
	v_add_u32_e32 v6, s8, v3
	v_cmp_gt_i32_e32 vcc, s20, v6
	v_cndmask_b32_e64 v5, 0, 1, s[6:7]
	s_and_b64 s[22:23], vcc, s[4:5]
	v_mov_b32_e32 v0, 0
	v_cmp_ne_u32_e64 s[6:7], 1, v5
	v_mov_b32_e32 v5, 0
	s_waitcnt lgkmcnt(0)
	s_barrier
	v_ashrrev_i32_e32 v7, 31, v6
	v_lshl_add_u64 v[212:213], v[6:7], 2, s[82:83]
	v_mov_b32_e32 v208, v6
	v_cmp_gt_i32_e64 s[46:47], s20, v208
	v_mad_u64_u32 v[192:193], s[50:51], v208, s18, 0
	v_ashrrev_i32_e32 v209, 31, v208
	v_mov_b32_e32 v210, v193
	v_mov_b32_e32 v211, v1
	s_and_b64 s[46:47], s[46:47], s[4:5]
	v_mad_u64_u32 v[210:211], s[50:51], v209, s18, v[210:211]
	v_mov_b32_e32 v176, 0
	v_mov_b32_e32 v193, v210
	v_mov_b32_e32 v184, 1.0
	v_lshl_add_u64 v[192:193], v[192:193], 2, v[8:9]
	s_and_saveexec_b64 s[48:49], s[46:47]
	global_load_dword v176, v[192:193], off
	s_and_b64 vcc, exec, s[6:7]
	s_cbranch_vccnz .Lcv2_nk0
	global_load_dword v184, v[212:213], off
.Lcv2_nk0:
	s_or_b64 exec, exec, s[48:49]
	v_add_u32_e32 v208, 8, v6
	v_cmp_gt_i32_e64 s[46:47], s20, v208
	v_mad_u64_u32 v[194:195], s[50:51], v208, s18, 0
	v_ashrrev_i32_e32 v209, 31, v208
	v_mov_b32_e32 v210, v195
	v_mov_b32_e32 v211, v1
	s_and_b64 s[46:47], s[46:47], s[4:5]
	v_mad_u64_u32 v[210:211], s[50:51], v209, s18, v[210:211]
	v_mov_b32_e32 v177, 0
	v_mov_b32_e32 v195, v210
	v_mov_b32_e32 v185, 1.0
	v_lshl_add_u64 v[194:195], v[194:195], 2, v[8:9]
	s_and_saveexec_b64 s[48:49], s[46:47]
	global_load_dword v177, v[194:195], off
	s_and_b64 vcc, exec, s[6:7]
	s_cbranch_vccnz .Lcv2_nk1
	global_load_dword v185, v[212:213], off offset:32
.Lcv2_nk1:
	s_or_b64 exec, exec, s[48:49]
	v_add_u32_e32 v208, 16, v6
	v_cmp_gt_i32_e64 s[46:47], s20, v208
	v_mad_u64_u32 v[196:197], s[50:51], v208, s18, 0
	v_ashrrev_i32_e32 v209, 31, v208
	v_mov_b32_e32 v210, v197
	v_mov_b32_e32 v211, v1
	s_and_b64 s[46:47], s[46:47], s[4:5]
	v_mad_u64_u32 v[210:211], s[50:51], v209, s18, v[210:211]
	v_mov_b32_e32 v178, 0
	v_mov_b32_e32 v197, v210
	v_mov_b32_e32 v186, 1.0
	v_lshl_add_u64 v[196:197], v[196:197], 2, v[8:9]
	s_and_saveexec_b64 s[48:49], s[46:47]
	global_load_dword v178, v[196:197], off
	s_and_b64 vcc, exec, s[6:7]
	s_cbranch_vccnz .Lcv2_nk2
	global_load_dword v186, v[212:213], off offset:64
.Lcv2_nk2:
	s_or_b64 exec, exec, s[48:49]
	v_add_u32_e32 v208, 24, v6
	v_cmp_gt_i32_e64 s[46:47], s20, v208
	v_mad_u64_u32 v[198:199], s[50:51], v208, s18, 0
	v_ashrrev_i32_e32 v209, 31, v208
	v_mov_b32_e32 v210, v199
	v_mov_b32_e32 v211, v1
	s_and_b64 s[46:47], s[46:47], s[4:5]
	v_mad_u64_u32 v[210:211], s[50:51], v209, s18, v[210:211]
	v_mov_b32_e32 v179, 0
	v_mov_b32_e32 v199, v210
	v_mov_b32_e32 v187, 1.0
	v_lshl_add_u64 v[198:199], v[198:199], 2, v[8:9]
	s_and_saveexec_b64 s[48:49], s[46:47]
	global_load_dword v179, v[198:199], off
	s_and_b64 vcc, exec, s[6:7]
	s_cbranch_vccnz .Lcv2_nk3
	global_load_dword v187, v[212:213], off offset:96
.Lcv2_nk3:
	s_or_b64 exec, exec, s[48:49]
	v_add_u32_e32 v208, 32, v6
	v_cmp_gt_i32_e64 s[46:47], s20, v208
	v_mad_u64_u32 v[200:201], s[50:51], v208, s18, 0
	v_ashrrev_i32_e32 v209, 31, v208
	v_mov_b32_e32 v210, v201
	v_mov_b32_e32 v211, v1
	s_and_b64 s[46:47], s[46:47], s[4:5]
	v_mad_u64_u32 v[210:211], s[50:51], v209, s18, v[210:211]
	v_mov_b32_e32 v180, 0
	v_mov_b32_e32 v201, v210
	v_mov_b32_e32 v188, 1.0
	v_lshl_add_u64 v[200:201], v[200:201], 2, v[8:9]
	s_and_saveexec_b64 s[48:49], s[46:47]
	global_load_dword v180, v[200:201], off
	s_and_b64 vcc, exec, s[6:7]
	s_cbranch_vccnz .Lcv2_nk4
	global_load_dword v188, v[212:213], off offset:128
.Lcv2_nk4:
	s_or_b64 exec, exec, s[48:49]
	v_add_u32_e32 v208, 40, v6
	v_cmp_gt_i32_e64 s[46:47], s20, v208
	v_mad_u64_u32 v[202:203], s[50:51], v208, s18, 0
	v_ashrrev_i32_e32 v209, 31, v208
	v_mov_b32_e32 v210, v203
	v_mov_b32_e32 v211, v1
	s_and_b64 s[46:47], s[46:47], s[4:5]
	v_mad_u64_u32 v[210:211], s[50:51], v209, s18, v[210:211]
	v_mov_b32_e32 v181, 0
	v_mov_b32_e32 v203, v210
	v_mov_b32_e32 v189, 1.0
	v_lshl_add_u64 v[202:203], v[202:203], 2, v[8:9]
	s_and_saveexec_b64 s[48:49], s[46:47]
	global_load_dword v181, v[202:203], off
	s_and_b64 vcc, exec, s[6:7]
	s_cbranch_vccnz .Lcv2_nk5
	global_load_dword v189, v[212:213], off offset:160
.Lcv2_nk5:
	s_or_b64 exec, exec, s[48:49]
	v_add_u32_e32 v208, 48, v6
	v_cmp_gt_i32_e64 s[46:47], s20, v208
	v_mad_u64_u32 v[204:205], s[50:51], v208, s18, 0
	v_ashrrev_i32_e32 v209, 31, v208
	v_mov_b32_e32 v210, v205
	v_mov_b32_e32 v211, v1
	s_and_b64 s[46:47], s[46:47], s[4:5]
	v_mad_u64_u32 v[210:211], s[50:51], v209, s18, v[210:211]
	v_mov_b32_e32 v182, 0
	v_mov_b32_e32 v205, v210
	v_mov_b32_e32 v190, 1.0
	v_lshl_add_u64 v[204:205], v[204:205], 2, v[8:9]
	s_and_saveexec_b64 s[48:49], s[46:47]
	global_load_dword v182, v[204:205], off
	s_and_b64 vcc, exec, s[6:7]
	s_cbranch_vccnz .Lcv2_nk6
	global_load_dword v190, v[212:213], off offset:192
.Lcv2_nk6:
	s_or_b64 exec, exec, s[48:49]
	v_add_u32_e32 v208, 56, v6
	v_cmp_gt_i32_e64 s[46:47], s20, v208
	v_mad_u64_u32 v[206:207], s[50:51], v208, s18, 0
	v_ashrrev_i32_e32 v209, 31, v208
	v_mov_b32_e32 v210, v207
	v_mov_b32_e32 v211, v1
	s_and_b64 s[46:47], s[46:47], s[4:5]
	v_mad_u64_u32 v[210:211], s[50:51], v209, s18, v[210:211]
	v_mov_b32_e32 v183, 0
	v_mov_b32_e32 v207, v210
	v_mov_b32_e32 v191, 1.0
	v_lshl_add_u64 v[206:207], v[206:207], 2, v[8:9]
	s_and_saveexec_b64 s[48:49], s[46:47]
	global_load_dword v183, v[206:207], off
	s_and_b64 vcc, exec, s[6:7]
	s_cbranch_vccnz .Lcv2_nk7
	global_load_dword v191, v[212:213], off offset:224

; __device__ __forceinline__ unsigned pk2(float lo, float hi) { const f2_t v = {lo, hi}; return __builtin_bit_cast(unsigned, __builtin_convertvector(v, bf2_t)); }
; __device__ void convert_phase(const Params& p, int l, int tbeg, int tend, float* sm, int w0) {
;     ...
;     __syncthreads();
;     { const int nn = tid >> 3, kk0 = (tid & 7) * 8; u32x4 w;
;       w.x = pk2(sm[(kk0 + 0) * 65 + nn], sm[(kk0 + 1) * 65 + nn]); w.y = pk2(sm[(kk0 + 2) * 65 + nn], sm[(kk0 + 3) * 65 + nn]);
;       w.z = pk2(sm[(kk0 + 4) * 65 + nn], sm[(kk0 + 5) * 65 + nn]); w.w = pk2(sm[(kk0 + 6) * 65 + nn], sm[(kk0 + 7) * 65 + nn]);
;       *(u32x4*)(dst + (long)(n0 + nn) * Kp + k0 + kk0) = w; }
.LBB0_1128:
	s_waitcnt lgkmcnt(0)
	s_barrier
	ds_read2_b32 v[6:7], v11 offset1:65
	ds_read2_b32 v[8:9], v11 offset0:130 offset1:195
	v_add_u32_e32 v0, 0x400, v11
	ds_read2_b32 v[14:15], v0 offset0:134 offset1:199
	s_add_i32 s2, s2, s62
	s_waitcnt lgkmcnt(2)
	v_cvt_pk_bf16_f32 v6, v6, v7
	s_waitcnt lgkmcnt(1)
	v_cvt_pk_bf16_f32 v7, v8, v9
	ds_read2_b32 v[8:9], v0 offset0:4 offset1:69
	v_add_u32_e32 v0, s9, v10
	v_ashrrev_i32_e32 v5, 31, v0
	v_mul_lo_u32 v5, s80, v5
	v_mul_lo_u32 v13, s81, v0
	s_waitcnt lgkmcnt(0)
	v_cvt_pk_bf16_f32 v8, v8, v9
	v_cvt_pk_bf16_f32 v9, v14, v15
	v_mad_u64_u32 v[14:15], s[4:5], s80, v0, 0
	v_add3_u32 v15, v15, v5, v13
	v_lshl_add_u64 v[14:15], v[14:15], 1, s[0:1]
	s_ashr_i32 s9, s8, 31
	v_lshl_add_u64 v[14:15], s[8:9], 1, v[14:15]
	v_mov_b32_e32 v5, v1
	s_add_i32 s17, s17, s62
	s_add_i32 s0, s2, 0x370
	v_lshl_add_u64 v[14:15], v[14:15], 0, v[4:5]
	s_cmpk_lt_i32 s0, 0x8f0
	global_store_dwordx4 v[14:15], v[6:9], off
	s_cbranch_scc0 .LBB0_1174

; __device__ void convert_phase(const Params& p, int l, int tbeg, int tend, float* sm, int w0) {
;     ...
;     const int n0 = (tt / nkt) * 64, k0 = (tt % nkt) * 64;
;     int c0 = n0;
;     if (mode == 1) { const int pn = n0 >> 8, j = n0 & 255; c0 = j < 128 ? pn * 128 + j : 2816 + pn * 128 + (j - 128); }
;     __syncthreads();
; #pragma unroll
;     for (int i = 0; i < 8; ++i) {
;       const int kk = (tid >> 6) + 8 * i, nn = tid & 63; float v = 0.f;
;       if (k0 + kk < K && n0 + nn < N) { v = src[(long)(k0 + kk) * N + c0 + nn]; if (ksc) v *= ksc[k0 + kk]; }
;       sm[kk * 65 + nn] = v;
;     }
.LBB0_1148:
	s_mul_i32 s8, s8, s21
	s_sub_i32 s4, s11, s8
	s_ashr_i32 s11, s10, 31
	s_lshl_b32 s8, s4, 6
	s_lshl_b64 s[10:11], s[10:11], 2
	s_add_u32 s6, s6, s10
	v_or_b32_e32 v0, s9, v2
	s_addc_u32 s7, s7, s11
	v_cmp_gt_i32_e64 s[4:5], s18, v0
	v_lshlrev_b32_e32 v0, 2, v2
	s_cmp_lg_u64 s[82:83], 0
	v_lshl_add_u64 v[8:9], s[6:7], 0, v[0:1]
	s_cselect_b64 s[6:7], -1, 0
	v_add_u32_e32 v6, s8, v3
	v_cmp_gt_i32_e32 vcc, s20, v6
	v_cndmask_b32_e64 v5, 0, 1, s[6:7]
	s_and_b64 s[22:23], vcc, s[4:5]
	v_mov_b32_e32 v0, 0
	v_cmp_ne_u32_e64 s[6:7], 1, v5
	v_mov_b32_e32 v5, 0
	s_waitcnt lgkmcnt(0)
	s_barrier
	v_ashrrev_i32_e32 v7, 31, v6
	v_lshl_add_u64 v[212:213], v[6:7], 2, s[82:83]
	v_mov_b32_e32 v208, v6
	v_cmp_gt_i32_e64 s[46:47], s20, v208
	v_mad_u64_u32 v[192:193], s[50:51], v208, s18, 0
	v_ashrrev_i32_e32 v209, 31, v208
	v_mov_b32_e32 v210, v193
	v_mov_b32_e32 v211, v1
	s_and_b64 s[46:47], s[46:47], s[4:5]
	v_mad_u64_u32 v[210:211], s[50:51], v209, s18, v[210:211]
	v_mov_b32_e32 v176, 0
	v_mov_b32_e32 v193, v210
	v_mov_b32_e32 v184, 1.0
	v_lshl_add_u64 v[192:193], v[192:193], 2, v[8:9]
	s_and_saveexec_b64 s[48:49], s[46:47]
	global_load_dword v176, v[192:193], off
	s_and_b64 vcc, exec, s[6:7]
	s_cbranch_vccnz .Lcv3_nk0
	global_load_dword v184, v[212:213], off
